# v11 + P2 pre-pass: KRF and rope-table loads of both row groups issued at the top of the phase
# baseline (speedup 1.0000x reference)
.LBB0_388:
	s_cmp_lt_i32 s84, 3
	s_cselect_b64 s[0:1], -1, 0
	s_cmp_gt_i32 s85, 2
	s_cselect_b64 s[2:3], -1, 0
	s_and_b64 s[0:1], s[0:1], s[2:3]
	s_andn2_b64 vcc, exec, s[0:1]
	s_cbranch_vccnz .LBB0_544
	s_ashr_i32 s0, s73, 31
	s_lshr_b32 s0, s0, 29
	s_add_i32 s0, s73, s0
	s_and_b32 s1, s0, 0x1ffffff8
	s_sub_i32 s1, s73, s1
	s_ashr_i32 s2, s0, 5
	s_lshl_b32 s1, s1, 3
	s_and_b32 s30, s2, -2
	s_add_i32 s30, s30, s1
	s_bfe_u32 s31, s0, 0x30003
	s_cmp_eq_u32 s31, 1
	s_cselect_b64 s[0:1], -1, 0
	s_cmp_gt_u32 s31, 4
	s_cselect_b64 s[2:3], -1, 0
	s_or_b64 s[0:1], s[0:1], s[2:3]
	v_cndmask_b32_e64 v0, 0, 1, s[0:1]
	s_mov_b64 s[4:5], s[82:83]
	v_readfirstlane_b32 s0, v0
	s_or_b32 s6, s30, s0
	v_mbcnt_lo_u32_b32 v0, -1, 0
	v_mbcnt_hi_u32_b32 v0, -1, v0
	s_movk_i32 s0, 0xff
	v_add_u32_e32 v2, s54, v0
	s_cmp_lt_u32 s31, 5
	s_cselect_b32 s98, -1, -4
	s_add_i32 s98, s98, s31
	s_cmp_lt_u32 s31, 2
	s_cselect_b32 s98, 0, s98
	s_mov_b32 s100, s6
	s_ashr_i32 s101, s6, 31
	s_lshl_b64 s[100:101], s[100:101], 8
	s_lshl_b32 s98, s98, 6
	s_ashr_i32 s99, s98, 31
	s_add_u32 s100, s100, s98
	s_addc_u32 s101, s101, s99
	s_add_u32 s98, s4, 0xc00000
	s_addc_u32 s99, s5, 0
	v_and_b32_e32 v4, 15, v0
	v_ashrrev_i32_e32 v6, 4, v2
	v_add_u32_e32 v12, 0x200, v2
	v_ashrrev_i32_e32 v7, 31, v6
	v_ashrrev_i32_e32 v12, 4, v12
	v_lshl_add_u64 v[6:7], s[100:101], 0, v[6:7]
	v_ashrrev_i32_e32 v13, 31, v12
	v_lshlrev_b64 v[8:9], 5, v[6:7]
	v_lshl_add_u64 v[12:13], s[100:101], 0, v[12:13]
	v_or_b32_e32 v8, v8, v4
	v_lshlrev_b64 v[14:15], 5, v[12:13]
	v_lshl_add_u64 v[8:9], v[8:9], 2, s[98:99]
	v_or_b32_e32 v14, v14, v4
	global_load_dword v247, v[8:9], off
	global_load_dword v248, v[8:9], off offset:64
	v_lshl_add_u64 v[14:15], v[14:15], 2, s[98:99]
	global_load_dword v249, v[14:15], off
	global_load_dword v252, v[14:15], off offset:64
	s_add_u32 s98, s4, 0x100000
	s_addc_u32 s99, s5, 0
	v_lshlrev_b32_e32 v10, 3, v4
	v_mov_b32_e32 v11, 0
	v_lshlrev_b64 v[6:7], 7, v[6:7]
	v_lshl_add_u64 v[10:11], s[98:99], 0, v[10:11]
	v_lshlrev_b64 v[12:13], 7, v[12:13]
	v_lshl_add_u64 v[6:7], v[10:11], 0, v[6:7]
	v_lshl_add_u64 v[12:13], v[10:11], 0, v[12:13]
	global_load_dwordx2 v[250:251], v[6:7], off
	global_load_dwordx2 v[254:255], v[12:13], off
	v_cmp_lt_i32_e32 vcc, s0, v2
	s_and_saveexec_b64 s[0:1], vcc
	s_xor_b64 s[2:3], exec, s[0:1]
	s_cbranch_execz .LBB0_391
	v_add_u32_e32 v1, 0xffffff00, v2
	v_lshl_add_u32 v4, s6, 8, v1
	v_ashrrev_i32_e32 v5, 31, v4
	v_lshlrev_b64 v[4:5], 5, v[4:5]
	v_lshl_add_u64 v[4:5], s[4:5], 0, v[4:5]
	v_add_co_u32_e32 v14, vcc, 0x400000, v4
	s_mov_b64 s[0:1], 0x400000
	s_nop 0
	v_addc_co_u32_e32 v15, vcc, 0, v5, vcc
	v_lshl_add_u64 v[12:13], v[4:5], 0, s[0:1]
	global_load_dwordx4 v[4:7], v[14:15], off
	global_load_dwordx4 v[8:11], v[12:13], off offset:16
	v_mov_b32_e32 v3, 0x358637bd
	s_mov_b32 s0, 0xf800000
	v_lshl_add_u32 v1, v1, 2, 0
	v_add_u32_e32 v1, 0x20c00, v1
	s_waitcnt vmcnt(1)
	v_mov_b32_e32 v12, v4
	s_waitcnt vmcnt(0)
	v_mov_b32_e32 v13, v8
	v_mov_b32_e32 v8, v5
	v_mov_b32_e32 v4, v6
	v_mov_b32_e32 v5, v10
	v_mov_b32_e32 v10, v7
	v_pk_add_f32 v[6:7], v[12:13], v[8:9]
	v_pk_add_f32 v[4:5], v[4:5], v[10:11]
	s_nop 0
	v_pk_add_f32 v[4:5], v[6:7], v[4:5]
	s_nop 0
	v_add_f32_e32 v4, v4, v5
	v_fmac_f32_e32 v3, 0x3b800000, v4
	v_mul_f32_e32 v4, 0x4f800000, v3
	v_cmp_gt_f32_e32 vcc, s0, v3
	v_mov_b32_e32 v5, 0x260
	s_nop 0
	v_cndmask_b32_e32 v3, v3, v4, vcc
	v_sqrt_f32_e32 v4, v3
	s_nop 0
	v_add_u32_e32 v6, -1, v4
	v_add_u32_e32 v7, 1, v4
	v_fma_f32 v8, -v6, v4, v3
	v_fma_f32 v9, -v7, v4, v3
	v_cmp_ge_f32_e64 s[0:1], 0, v8
	s_nop 1
	v_cndmask_b32_e64 v4, v4, v6, s[0:1]
	v_cmp_lt_f32_e64 s[0:1], 0, v9
	s_nop 1
	v_cndmask_b32_e64 v4, v4, v7, s[0:1]
	v_mul_f32_e32 v6, 0x37800000, v4
	v_cndmask_b32_e32 v4, v4, v6, vcc
	v_cmp_class_f32_e32 vcc, v3, v5
	s_nop 1
	v_cndmask_b32_e32 v3, v4, v3, vcc
	v_div_scale_f32 v4, s[0:1], v3, v3, 1.0
	v_rcp_f32_e32 v5, v4
	v_div_scale_f32 v6, vcc, 1.0, v3, 1.0
	v_fma_f32 v7, -v4, v5, 1.0
	v_fmac_f32_e32 v5, v7, v5
	v_mul_f32_e32 v7, v6, v5
	v_fma_f32 v8, -v4, v7, v6
	v_fmac_f32_e32 v7, v8, v5
	v_fma_f32 v4, -v4, v7, v6
	v_div_fmas_f32 v4, v4, v5, v7
	v_div_fixup_f32 v3, v4, v3, 1.0
	ds_write_b32 v1, v3

.LBB0_393:
	s_or_b64 exec, exec, s[2:3]
	s_add_u32 s2, s4, 0xc00000
	s_addc_u32 s3, s5, 0
	s_add_u32 s0, s4, 0xfb00000
	s_addc_u32 s1, s5, 0
	s_cmp_gt_u32 s31, 1
	s_cselect_b64 s[10:11], -1, 0
	s_cmp_lt_u32 s31, 5
	s_cselect_b32 s7, -1, -4
	s_add_i32 s7, s7, s31
	s_cmp_lt_u32 s31, 2
	s_cselect_b64 s[8:9], -1, 0
	s_and_b64 s[12:13], s[8:9], exec
	s_cselect_b32 s18, 0, s7
	s_ashr_i32 s7, s6, 31
	s_lshl_b64 s[12:13], s[6:7], 8
	s_lshl_b32 s7, s18, 6
	s_ashr_i32 s14, s7, 31
	v_and_b32_e32 v3, 15, v0
	s_add_u32 s12, s12, s7
	v_ashrrev_i32_e32 v0, 4, v2
	s_addc_u32 s13, s13, s14
	v_ashrrev_i32_e32 v1, 31, v0
	v_lshl_add_u64 v[4:5], s[12:13], 0, v[0:1]
	v_lshlrev_b64 v[6:7], 5, v[4:5]
	v_or_b32_e32 v6, v6, v3
	v_or_b32_e32 v8, 16, v6
	v_mov_b32_e32 v9, v7
	v_lshl_add_u64 v[10:11], v[8:9], 2, s[2:3]
	v_lshl_add_u64 v[0:1], v[6:7], 2, s[2:3]
	v_mov_b32_e32 v12, v248
	v_mov_b32_e32 v13, v247
	v_mov_b32_e32 v1, 0
	v_lshlrev_b32_e32 v0, 3, v3
	v_lshl_add_u64 v[0:1], s[4:5], 0, v[0:1]
	s_mov_b64 s[14:15], 0x100000
	v_lshl_add_u64 v[0:1], v[0:1], 0, s[14:15]
	v_lshlrev_b64 v[4:5], 7, v[4:5]
	v_lshl_add_u64 v[4:5], v[0:1], 0, v[4:5]
	v_mov_b32_e32 v10, v250
	v_mov_b32_e32 v11, v251
	v_mbcnt_lo_u32_b32 v4, -1, 0
	v_mbcnt_hi_u32_b32 v4, -1, v4
	v_and_b32_e32 v14, 64, v4
	v_xor_b32_e32 v5, 1, v4
	v_add_u32_e32 v14, 64, v14
	v_cmp_lt_i32_e32 vcc, v5, v14
	v_xor_b32_e32 v17, 32, v4
	s_movk_i32 s14, 0x7fff
	v_cndmask_b32_e32 v5, v4, v5, vcc
	v_lshlrev_b32_e32 v146, 2, v5
	v_xor_b32_e32 v5, 2, v4
	v_cmp_lt_i32_e32 vcc, v5, v14
	v_lshl_add_u64 v[6:7], v[6:7], 1, s[0:1]
	v_lshl_add_u64 v[8:9], v[8:9], 1, s[0:1]
	v_cndmask_b32_e32 v5, v4, v5, vcc
	v_lshlrev_b32_e32 v147, 2, v5
	v_xor_b32_e32 v5, 4, v4
	v_cmp_lt_i32_e32 vcc, v5, v14
	s_mov_b32 s7, 0
	s_waitcnt vmcnt(2)
	v_mul_f32_e32 v15, v12, v12
	s_waitcnt vmcnt(1)
	v_fmac_f32_e32 v15, v13, v13
	ds_bpermute_b32 v16, v146, v15
	v_cndmask_b32_e32 v5, v4, v5, vcc
	v_lshlrev_b32_e32 v148, 2, v5
	v_xor_b32_e32 v5, 8, v4
	v_cmp_lt_i32_e32 vcc, v5, v14
	s_waitcnt lgkmcnt(0)
	v_add_f32_e32 v15, v15, v16
	ds_bpermute_b32 v16, v147, v15
	v_cndmask_b32_e32 v5, v4, v5, vcc
	v_lshlrev_b32_e32 v149, 2, v5
	v_xor_b32_e32 v5, 16, v4
	v_cmp_lt_i32_e32 vcc, v5, v14
	s_nop 1
	v_cndmask_b32_e32 v5, v4, v5, vcc
	v_cmp_lt_i32_e32 vcc, v17, v14
	s_waitcnt lgkmcnt(0)
	v_add_f32_e32 v14, v15, v16
	ds_bpermute_b32 v15, v148, v14
	s_waitcnt vmcnt(0)
	v_mul_f32_e32 v16, v12, v11
	v_fma_f32 v16, v13, v10, -v16
	v_cndmask_b32_e32 v4, v4, v17, vcc
	v_bfe_u32 v17, v16, 16, 1
	s_waitcnt lgkmcnt(0)
	v_add_f32_e32 v14, v14, v15
	ds_bpermute_b32 v15, v149, v14
	v_add3_u32 v16, v16, v17, s14
	v_lshlrev_b32_e32 v5, 2, v5
	global_store_short_d16_hi v[6:7], v16, off
	v_lshlrev_b32_e32 v4, 2, v4
	s_waitcnt lgkmcnt(0)
	v_add_f32_e32 v6, v14, v15
	ds_bpermute_b32 v7, v5, v6
	v_mul_f32_e32 v11, v13, v11
	v_fmac_f32_e32 v11, v12, v10
	v_bfe_u32 v10, v11, 16, 1
	v_add3_u32 v10, v11, v10, s14
	s_waitcnt lgkmcnt(0)
	v_max_f32_e32 v7, v7, v7
	v_max_f32_e32 v6, v6, v7
	ds_bpermute_b32 v7, v4, v6
	global_store_short_d16_hi v[8:9], v10, off
	v_mbcnt_lo_u32_b32 v8, -1, 0
	v_mbcnt_hi_u32_b32 v8, -1, v8
	s_nop 0
	v_cmp_eq_u32_e32 vcc, 0, v8
	s_and_saveexec_b64 s[14:15], vcc
	s_cbranch_execz .LBB0_398
	s_waitcnt lgkmcnt(0)
	v_max_f32_e32 v7, v7, v7
	v_max_f32_e32 v6, v6, v6
	s_mov_b64 s[16:17], exec
	v_max_f32_e32 v6, v6, v7

.LBB0_398:
	s_or_b64 exec, exec, s[14:15]
	v_add_u32_e32 v6, 0x200, v2
	v_ashrrev_i32_e32 v6, 4, v6
	s_waitcnt lgkmcnt(0)
	v_ashrrev_i32_e32 v7, 31, v6
	v_lshl_add_u64 v[6:7], s[12:13], 0, v[6:7]
	v_lshlrev_b64 v[8:9], 5, v[6:7]
	v_or_b32_e32 v8, v8, v3
	v_or_b32_e32 v12, 16, v8
	v_mov_b32_e32 v13, v9
	v_lshl_add_u64 v[14:15], v[12:13], 2, s[2:3]
	v_lshl_add_u64 v[10:11], v[8:9], 2, s[2:3]
	v_mov_b32_e32 v3, v252
	v_mov_b32_e32 v16, v249
	v_lshlrev_b64 v[6:7], 7, v[6:7]
	v_lshl_add_u64 v[0:1], v[0:1], 0, v[6:7]
	v_mov_b32_e32 v0, v254
	v_mov_b32_e32 v1, v255
	s_movk_i32 s2, 0x7fff
	s_mov_b32 s7, 0
	s_waitcnt vmcnt(2)
	v_mul_f32_e32 v6, v3, v3
	s_waitcnt vmcnt(1)
	v_fmac_f32_e32 v6, v16, v16
	ds_bpermute_b32 v7, v146, v6
	s_waitcnt vmcnt(0)
	v_mul_f32_e32 v10, v3, v1
	v_mul_f32_e32 v1, v16, v1
	v_fmac_f32_e32 v1, v3, v0
	s_waitcnt lgkmcnt(0)
	v_add_f32_e32 v6, v6, v7
	ds_bpermute_b32 v7, v147, v6
	v_fma_f32 v10, v16, v0, -v10
	v_bfe_u32 v0, v1, 16, 1
	v_add3_u32 v3, v1, v0, s2
	v_bfe_u32 v11, v10, 16, 1
	s_waitcnt lgkmcnt(0)
	v_add_f32_e32 v6, v6, v7
	ds_bpermute_b32 v7, v148, v6
	v_add3_u32 v10, v10, v11, s2
	s_waitcnt lgkmcnt(0)
	v_add_f32_e32 v14, v6, v7
	ds_bpermute_b32 v15, v149, v14
	v_lshl_add_u64 v[6:7], v[8:9], 1, s[0:1]
	global_store_short_d16_hi v[6:7], v10, off
	v_lshl_add_u64 v[6:7], v[12:13], 1, s[0:1]
	global_store_short_d16_hi v[6:7], v3, off
	s_waitcnt lgkmcnt(0)
	v_add_f32_e32 v8, v14, v15
	ds_bpermute_b32 v5, v5, v8
	v_mbcnt_lo_u32_b32 v3, -1, 0
	v_mbcnt_hi_u32_b32 v3, -1, v3
	s_waitcnt lgkmcnt(0)
	v_max_f32_e32 v0, v5, v5
	v_max_f32_e32 v0, v8, v0
	ds_bpermute_b32 v1, v4, v0
	v_cmp_eq_u32_e32 vcc, 0, v3
	s_and_saveexec_b64 s[0:1], vcc
	s_cbranch_execz .LBB0_403
	s_waitcnt lgkmcnt(0)
	v_max_f32_e32 v1, v1, v1
	v_max_f32_e32 v0, v0, v0
	s_mov_b64 s[2:3], exec
	v_max_f32_e32 v0, v0, v1
